# thin-GEMM loads de-serialised + kv_prompt_out fast path + deferred DN transposition (nt) + lru_conv_own rows de-serialised + EpiUpGlu prefetch vmcnt(0) removed
# speedup vs baseline: 1.0046x; 1.0046x over previous
;     __device__ __forceinline__ Pre prefetch(const Unit& u, int tid) const { Pre p; pre_row_load(p.r, SSP, u.pm, tid); p.c = (MODE == 1 && tid < 256) ? bias[u.pn * BM + tid] : 0.f; return p; }
;     __device__ __forceinline__ Pre prefetch(const Unit& u, int tid) const { Pre p; pre_row_load(p, SSP, u.pm, tid); return p; }
;     __device__ __forceinline__ Pre prefetch(const Unit& u, int tid) const {
;         Pre p;
;         if (tid < 256) { const float* sp = SSP + (size_t)(u.pm * BM + tid) * 8; p.a = *(const f32x4*)sp; p.b = *(const f32x4*)(sp + 4); }
;         else { const int i = tid - 256, arr = i >> 5, c4 = (i & 31) * 4; const int k = arr < 3 ? arr : arr - 3;
;             const size_t off = (arr < 6 ? (size_t)k * 12288 : (size_t)0) + ((arr >= 3 && arr != 6) ? 6144 : 0) + (size_t)u.pn * 128 + c4;
;             const float* base = arr < 6 ? cw : cb; p.a = *(const f32x4*)(base + off); p.b = p.a; }
;         return p;
.LBB0_771:
	s_or_saveexec_b64 s[2:3], s[2:3]
	s_xor_b64 exec, exec, s[2:3]
	s_cbranch_execz .LBB0_773
	v_lshl_add_u32 v2, s10, 8, v177
	v_ashrrev_i32_e32 v3, 31, v2
	v_lshlrev_b64 v[2:3], 5, v[2:3]
	v_lshl_add_u64 v[2:3], s[0:1], 0, v[2:3]
	global_load_dwordx4 v[78:81], v[2:3], off offset:16
	global_load_dwordx4 v[74:77], v[2:3], off

;     __device__ __forceinline__ Pre prefetch(const Unit& u, int tid) const { Pre p; pre_row_load(p.r, SSP, u.pm, tid); p.c = (MODE == 1 && tid < 256) ? bias[u.pn * BM + tid] : 0.f; return p; }
;     __device__ __forceinline__ Pre prefetch(const Unit& u, int tid) const { Pre p; pre_row_load(p, SSP, u.pm, tid); return p; }
;     __device__ __forceinline__ Pre prefetch(const Unit& u, int tid) const {
;         Pre p;
;         if (tid < 256) { const float* sp = SSP + (size_t)(u.pm * BM + tid) * 8; p.a = *(const f32x4*)sp; p.b = *(const f32x4*)(sp + 4); }
;         else { const int i = tid - 256, arr = i >> 5, c4 = (i & 31) * 4; const int k = arr < 3 ? arr : arr - 3;
;             const size_t off = (arr < 6 ? (size_t)k * 12288 : (size_t)0) + ((arr >= 3 && arr != 6) ? 6144 : 0) + (size_t)u.pn * 128 + c4;
;             const float* base = arr < 6 ? cw : cb; p.a = *(const f32x4*)(base + off); p.b = p.a; }
;         return p;
; template <class Epi, class Sched, bool ALIGN_EPI = false, bool SP2 = false>
; __device__ __forceinline__ void gemm_phase(PG8_LAS unsigned char* lds, const Gemm g, const Sched& S, const Epi& E, const int wv) {
;     ...
;         if constexpr (Epi::HAS_PRE) pre = E.prefetch(cur, tid);
.LBB0_804:
	s_or_saveexec_b64 s[10:11], s[10:11]
	s_xor_b64 exec, exec, s[10:11]
	s_cbranch_execz .LBB0_806
	v_lshl_add_u32 v2, s50, 8, v177
	v_ashrrev_i32_e32 v3, 31, v2
	v_lshlrev_b64 v[2:3], 5, v[2:3]
	v_lshl_add_u64 v[2:3], s[0:1], 0, v[2:3]
	global_load_dwordx4 v[78:81], v[2:3], off offset:16
	global_load_dwordx4 v[74:77], v[2:3], off
